# P5 EpiMerged epilogue hand-written: 16-byte gate/MG loads and stores via v_permlane16_swap, loads issued ahead with counted waits
# speedup vs baseline: 1.0113x; 1.0113x over previous
.LBB0_1142:
	s_and_b32 s2, s5, 1
	s_mul_i32 s3, s2, 0x2800000
	s_add_u32 s26, s64, s3
	s_addc_u32 s27, s65, 0
	s_lshr_b32 s3, s5, 1
	s_lshl_b32 s3, s3, 8
	s_lshl_b32 s18, s4, 8
	s_cmp_gt_i32 s76, 0
	s_cbranch_scc0 .Lp5_noq
	s_sub_i32 s34, s76, 1
	s_and_b32 s35, s34, 1
	s_lshl_b32 s35, s35, 7
	s_add_i32 s3, s3, s35
	s_lshr_b32 s34, s34, 1
	s_lshl_b32 s34, s34, 7
	s_add_i32 s18, s18, s34
.Lp5_noq:
	v_add_u32_e32 v1, s18, v210
	v_lshlrev_b32_e32 v1, 11, v1
	v_add3_u32 v1, v1, s3, v211
	v_lshlrev_b32_e32 v1, 1, v1
	v_bfe_u32 v204, v211, 2, 1
	v_mul_u32_u24_e32 v204, 24, v204
	v_add_u32_e32 v1, v1, v204
	s_cmp_gt_i32 s76, 0
	s_cbranch_scc1 .Lp5_quart
	s_cmp_eq_u32 s2, 0
	s_cbranch_scc0 .Lp5_full_seg1
	v_mov_b32_e32 v217, v1
	v_add_u32_e32 v218, 0x10000, v1
	v_add_u32_e32 v219, 0x20000, v1
	v_add_u32_e32 v220, 0x30000, v1
	v_add_u32_e32 v221, 0x80000, v1
	v_add_u32_e32 v222, 0x90000, v1
	v_add_u32_e32 v223, 0xa0000, v1
	v_add_u32_e32 v224, 0xb0000, v1
	global_load_dwordx4 v[132:135], v217, s[26:27] offset:0
	global_load_dwordx4 v[136:139], v217, s[26:27] offset:256
	global_load_dwordx4 v[140:143], v218, s[26:27] offset:0
	global_load_dwordx4 v[144:147], v218, s[26:27] offset:256
	global_load_dwordx4 v[148:151], v219, s[26:27] offset:0
	global_load_dwordx4 v[152:155], v219, s[26:27] offset:256
	global_load_dwordx4 v[156:159], v220, s[26:27] offset:0
	global_load_dwordx4 v[160:163], v220, s[26:27] offset:256
	global_load_dwordx4 v[164:167], v221, s[26:27] offset:0
	global_load_dwordx4 v[168:171], v221, s[26:27] offset:256
	global_load_dwordx4 v[172:175], v222, s[26:27] offset:0
	global_load_dwordx4 v[176:179], v222, s[26:27] offset:256
	global_load_dwordx4 v[180:183], v223, s[26:27] offset:0
	global_load_dwordx4 v[184:187], v223, s[26:27] offset:256
	global_load_dwordx4 v[188:191], v224, s[26:27] offset:0
	global_load_dwordx4 v[192:195], v224, s[26:27] offset:256
	s_waitcnt vmcnt(15)
	v_permlane16_swap_b32 v132, v134
	v_permlane16_swap_b32 v133, v135
	v_lshlrev_b32_e32 v204, 16, v132
	v_and_b32_e32 v205, 0xffff0000, v132
	v_lshlrev_b32_e32 v206, 16, v133
	v_and_b32_e32 v207, 0xffff0000, v133
	v_pk_mul_f32 v[128:129], v[128:129], v[204:205]
	v_pk_mul_f32 v[130:131], v[130:131], v[206:207]
	v_lshlrev_b32_e32 v204, 16, v134
	v_and_b32_e32 v205, 0xffff0000, v134
	v_lshlrev_b32_e32 v206, 16, v135
	v_and_b32_e32 v207, 0xffff0000, v135
	v_pk_mul_f32 v[124:125], v[124:125], v[204:205]
	v_pk_mul_f32 v[126:127], v[126:127], v[206:207]
	v_cvt_pk_bf16_f32 v226, v128, v129
	v_cvt_pk_bf16_f32 v227, v130, v131
	v_cvt_pk_bf16_f32 v228, v124, v125
	v_cvt_pk_bf16_f32 v229, v126, v127
	s_nop 1
	v_permlane16_swap_b32 v226, v228
	v_permlane16_swap_b32 v227, v229
	global_store_dwordx4 v217, v[226:229], s[14:15] offset:0
	s_waitcnt vmcnt(15)
	v_permlane16_swap_b32 v136, v138
	v_permlane16_swap_b32 v137, v139
	v_lshlrev_b32_e32 v204, 16, v136
	v_and_b32_e32 v205, 0xffff0000, v136
	v_lshlrev_b32_e32 v206, 16, v137
	v_and_b32_e32 v207, 0xffff0000, v137
	v_pk_mul_f32 v[112:113], v[112:113], v[204:205]
	v_pk_mul_f32 v[114:115], v[114:115], v[206:207]
	v_lshlrev_b32_e32 v204, 16, v138
	v_and_b32_e32 v205, 0xffff0000, v138
	v_lshlrev_b32_e32 v206, 16, v139
	v_and_b32_e32 v207, 0xffff0000, v139
	v_pk_mul_f32 v[108:109], v[108:109], v[204:205]
	v_pk_mul_f32 v[110:111], v[110:111], v[206:207]
	v_cvt_pk_bf16_f32 v230, v112, v113
	v_cvt_pk_bf16_f32 v231, v114, v115
	v_cvt_pk_bf16_f32 v232, v108, v109
	v_cvt_pk_bf16_f32 v233, v110, v111
	s_nop 1
	v_permlane16_swap_b32 v230, v232
	v_permlane16_swap_b32 v231, v233
	global_store_dwordx4 v217, v[230:233], s[14:15] offset:256
	s_waitcnt vmcnt(15)
	v_permlane16_swap_b32 v140, v142
	v_permlane16_swap_b32 v141, v143
	v_lshlrev_b32_e32 v204, 16, v140
	v_and_b32_e32 v205, 0xffff0000, v140
	v_lshlrev_b32_e32 v206, 16, v141
	v_and_b32_e32 v207, 0xffff0000, v141
	v_pk_mul_f32 v[120:121], v[120:121], v[204:205]
	v_pk_mul_f32 v[122:123], v[122:123], v[206:207]
	v_lshlrev_b32_e32 v204, 16, v142
	v_and_b32_e32 v205, 0xffff0000, v142
	v_lshlrev_b32_e32 v206, 16, v143
	v_and_b32_e32 v207, 0xffff0000, v143
	v_pk_mul_f32 v[116:117], v[116:117], v[204:205]
	v_pk_mul_f32 v[118:119], v[118:119], v[206:207]
	v_cvt_pk_bf16_f32 v244, v120, v121
	v_cvt_pk_bf16_f32 v245, v122, v123
	v_cvt_pk_bf16_f32 v246, v116, v117
	v_cvt_pk_bf16_f32 v247, v118, v119
	s_nop 1
	v_permlane16_swap_b32 v244, v246
	v_permlane16_swap_b32 v245, v247
	global_store_dwordx4 v218, v[244:247], s[14:15] offset:0
	s_waitcnt vmcnt(15)
	v_permlane16_swap_b32 v144, v146
	v_permlane16_swap_b32 v145, v147
	v_lshlrev_b32_e32 v204, 16, v144
	v_and_b32_e32 v205, 0xffff0000, v144
	v_lshlrev_b32_e32 v206, 16, v145
	v_and_b32_e32 v207, 0xffff0000, v145
	v_pk_mul_f32 v[96:97], v[96:97], v[204:205]
	v_pk_mul_f32 v[98:99], v[98:99], v[206:207]
	v_lshlrev_b32_e32 v204, 16, v146
	v_and_b32_e32 v205, 0xffff0000, v146
	v_lshlrev_b32_e32 v206, 16, v147
	v_and_b32_e32 v207, 0xffff0000, v147
	v_pk_mul_f32 v[92:93], v[92:93], v[204:205]
	v_pk_mul_f32 v[94:95], v[94:95], v[206:207]
	v_cvt_pk_bf16_f32 v248, v96, v97
	v_cvt_pk_bf16_f32 v249, v98, v99
	v_cvt_pk_bf16_f32 v250, v92, v93
	v_cvt_pk_bf16_f32 v251, v94, v95
	s_nop 1
	v_permlane16_swap_b32 v248, v250
	v_permlane16_swap_b32 v249, v251
	global_store_dwordx4 v218, v[248:251], s[14:15] offset:256
	s_waitcnt vmcnt(15)
	v_permlane16_swap_b32 v148, v150
	v_permlane16_swap_b32 v149, v151
	v_lshlrev_b32_e32 v204, 16, v148
	v_and_b32_e32 v205, 0xffff0000, v148
	v_lshlrev_b32_e32 v206, 16, v149
	v_and_b32_e32 v207, 0xffff0000, v149
	v_pk_mul_f32 v[104:105], v[104:105], v[204:205]
	v_pk_mul_f32 v[106:107], v[106:107], v[206:207]
	v_lshlrev_b32_e32 v204, 16, v150
	v_and_b32_e32 v205, 0xffff0000, v150
	v_lshlrev_b32_e32 v206, 16, v151
	v_and_b32_e32 v207, 0xffff0000, v151
	v_pk_mul_f32 v[100:101], v[100:101], v[204:205]
	v_pk_mul_f32 v[102:103], v[102:103], v[206:207]
	v_cvt_pk_bf16_f32 v226, v104, v105
	v_cvt_pk_bf16_f32 v227, v106, v107
	v_cvt_pk_bf16_f32 v228, v100, v101
	v_cvt_pk_bf16_f32 v229, v102, v103
	s_nop 1
	v_permlane16_swap_b32 v226, v228
	v_permlane16_swap_b32 v227, v229
	global_store_dwordx4 v219, v[226:229], s[14:15] offset:0
	s_waitcnt vmcnt(15)
	v_permlane16_swap_b32 v152, v154
	v_permlane16_swap_b32 v153, v155
	v_lshlrev_b32_e32 v204, 16, v152
	v_and_b32_e32 v205, 0xffff0000, v152
	v_lshlrev_b32_e32 v206, 16, v153
	v_and_b32_e32 v207, 0xffff0000, v153
	v_pk_mul_f32 v[80:81], v[80:81], v[204:205]
	v_pk_mul_f32 v[82:83], v[82:83], v[206:207]
	v_lshlrev_b32_e32 v204, 16, v154
	v_and_b32_e32 v205, 0xffff0000, v154
	v_lshlrev_b32_e32 v206, 16, v155
	v_and_b32_e32 v207, 0xffff0000, v155
	v_pk_mul_f32 v[76:77], v[76:77], v[204:205]
	v_pk_mul_f32 v[78:79], v[78:79], v[206:207]
	v_cvt_pk_bf16_f32 v230, v80, v81
	v_cvt_pk_bf16_f32 v231, v82, v83
	v_cvt_pk_bf16_f32 v232, v76, v77
	v_cvt_pk_bf16_f32 v233, v78, v79
	s_nop 1
	v_permlane16_swap_b32 v230, v232
	v_permlane16_swap_b32 v231, v233
	global_store_dwordx4 v219, v[230:233], s[14:15] offset:256
	s_waitcnt vmcnt(15)
	v_permlane16_swap_b32 v156, v158
	v_permlane16_swap_b32 v157, v159
	v_lshlrev_b32_e32 v204, 16, v156
	v_and_b32_e32 v205, 0xffff0000, v156
	v_lshlrev_b32_e32 v206, 16, v157
	v_and_b32_e32 v207, 0xffff0000, v157
	v_pk_mul_f32 v[88:89], v[88:89], v[204:205]
	v_pk_mul_f32 v[90:91], v[90:91], v[206:207]
	v_lshlrev_b32_e32 v204, 16, v158
	v_and_b32_e32 v205, 0xffff0000, v158
	v_lshlrev_b32_e32 v206, 16, v159
	v_and_b32_e32 v207, 0xffff0000, v159
	v_pk_mul_f32 v[84:85], v[84:85], v[204:205]
	v_pk_mul_f32 v[86:87], v[86:87], v[206:207]
	v_cvt_pk_bf16_f32 v244, v88, v89
	v_cvt_pk_bf16_f32 v245, v90, v91
	v_cvt_pk_bf16_f32 v246, v84, v85
	v_cvt_pk_bf16_f32 v247, v86, v87
	s_nop 1
	v_permlane16_swap_b32 v244, v246
	v_permlane16_swap_b32 v245, v247
	global_store_dwordx4 v220, v[244:247], s[14:15] offset:0
	s_waitcnt vmcnt(15)
	v_permlane16_swap_b32 v160, v162
	v_permlane16_swap_b32 v161, v163
	v_lshlrev_b32_e32 v204, 16, v160
	v_and_b32_e32 v205, 0xffff0000, v160
	v_lshlrev_b32_e32 v206, 16, v161
	v_and_b32_e32 v207, 0xffff0000, v161
	v_pk_mul_f32 v[72:73], v[72:73], v[204:205]
	v_pk_mul_f32 v[74:75], v[74:75], v[206:207]
	v_lshlrev_b32_e32 v204, 16, v162
	v_and_b32_e32 v205, 0xffff0000, v162
	v_lshlrev_b32_e32 v206, 16, v163
	v_and_b32_e32 v207, 0xffff0000, v163
	v_pk_mul_f32 v[68:69], v[68:69], v[204:205]
	v_pk_mul_f32 v[70:71], v[70:71], v[206:207]
	v_cvt_pk_bf16_f32 v248, v72, v73
	v_cvt_pk_bf16_f32 v249, v74, v75
	v_cvt_pk_bf16_f32 v250, v68, v69
	v_cvt_pk_bf16_f32 v251, v70, v71
	s_nop 1
	v_permlane16_swap_b32 v248, v250
	v_permlane16_swap_b32 v249, v251
	global_store_dwordx4 v220, v[248:251], s[14:15] offset:256
	s_waitcnt vmcnt(15)
	v_permlane16_swap_b32 v164, v166
	v_permlane16_swap_b32 v165, v167
	v_lshlrev_b32_e32 v204, 16, v164
	v_and_b32_e32 v205, 0xffff0000, v164
	v_lshlrev_b32_e32 v206, 16, v165
	v_and_b32_e32 v207, 0xffff0000, v165
	v_pk_mul_f32 v[64:65], v[64:65], v[204:205]
	v_pk_mul_f32 v[66:67], v[66:67], v[206:207]
	v_lshlrev_b32_e32 v204, 16, v166
	v_and_b32_e32 v205, 0xffff0000, v166
	v_lshlrev_b32_e32 v206, 16, v167
	v_and_b32_e32 v207, 0xffff0000, v167
	v_pk_mul_f32 v[60:61], v[60:61], v[204:205]
	v_pk_mul_f32 v[62:63], v[62:63], v[206:207]
	v_cvt_pk_bf16_f32 v226, v64, v65
	v_cvt_pk_bf16_f32 v227, v66, v67
	v_cvt_pk_bf16_f32 v228, v60, v61
	v_cvt_pk_bf16_f32 v229, v62, v63
	s_nop 1
	v_permlane16_swap_b32 v226, v228
	v_permlane16_swap_b32 v227, v229
	global_store_dwordx4 v221, v[226:229], s[14:15] offset:0
	s_waitcnt vmcnt(15)
	v_permlane16_swap_b32 v168, v170
	v_permlane16_swap_b32 v169, v171
	v_lshlrev_b32_e32 v204, 16, v168
	v_and_b32_e32 v205, 0xffff0000, v168
	v_lshlrev_b32_e32 v206, 16, v169
	v_and_b32_e32 v207, 0xffff0000, v169
	v_pk_mul_f32 v[56:57], v[56:57], v[204:205]
	v_pk_mul_f32 v[58:59], v[58:59], v[206:207]
	v_lshlrev_b32_e32 v204, 16, v170
	v_and_b32_e32 v205, 0xffff0000, v170
	v_lshlrev_b32_e32 v206, 16, v171
	v_and_b32_e32 v207, 0xffff0000, v171
	v_pk_mul_f32 v[52:53], v[52:53], v[204:205]
	v_pk_mul_f32 v[54:55], v[54:55], v[206:207]
	v_cvt_pk_bf16_f32 v230, v56, v57
	v_cvt_pk_bf16_f32 v231, v58, v59
	v_cvt_pk_bf16_f32 v232, v52, v53
	v_cvt_pk_bf16_f32 v233, v54, v55
	s_nop 1
	v_permlane16_swap_b32 v230, v232
	v_permlane16_swap_b32 v231, v233
	global_store_dwordx4 v221, v[230:233], s[14:15] offset:256
	s_waitcnt vmcnt(15)
	v_permlane16_swap_b32 v172, v174
	v_permlane16_swap_b32 v173, v175
	v_lshlrev_b32_e32 v204, 16, v172
	v_and_b32_e32 v205, 0xffff0000, v172
	v_lshlrev_b32_e32 v206, 16, v173
	v_and_b32_e32 v207, 0xffff0000, v173
	v_pk_mul_f32 v[48:49], v[48:49], v[204:205]
	v_pk_mul_f32 v[50:51], v[50:51], v[206:207]
	v_lshlrev_b32_e32 v204, 16, v174
	v_and_b32_e32 v205, 0xffff0000, v174
	v_lshlrev_b32_e32 v206, 16, v175
	v_and_b32_e32 v207, 0xffff0000, v175
	v_pk_mul_f32 v[44:45], v[44:45], v[204:205]
	v_pk_mul_f32 v[46:47], v[46:47], v[206:207]
	v_cvt_pk_bf16_f32 v244, v48, v49
	v_cvt_pk_bf16_f32 v245, v50, v51
	v_cvt_pk_bf16_f32 v246, v44, v45
	v_cvt_pk_bf16_f32 v247, v46, v47
	s_nop 1
	v_permlane16_swap_b32 v244, v246
	v_permlane16_swap_b32 v245, v247
	global_store_dwordx4 v222, v[244:247], s[14:15] offset:0
	s_waitcnt vmcnt(15)
	v_permlane16_swap_b32 v176, v178
	v_permlane16_swap_b32 v177, v179
	v_lshlrev_b32_e32 v204, 16, v176
	v_and_b32_e32 v205, 0xffff0000, v176
	v_lshlrev_b32_e32 v206, 16, v177
	v_and_b32_e32 v207, 0xffff0000, v177
	v_pk_mul_f32 v[40:41], v[40:41], v[204:205]
	v_pk_mul_f32 v[42:43], v[42:43], v[206:207]
	v_lshlrev_b32_e32 v204, 16, v178
	v_and_b32_e32 v205, 0xffff0000, v178
	v_lshlrev_b32_e32 v206, 16, v179
	v_and_b32_e32 v207, 0xffff0000, v179
	v_pk_mul_f32 v[36:37], v[36:37], v[204:205]
	v_pk_mul_f32 v[38:39], v[38:39], v[206:207]
	v_cvt_pk_bf16_f32 v248, v40, v41
	v_cvt_pk_bf16_f32 v249, v42, v43
	v_cvt_pk_bf16_f32 v250, v36, v37
	v_cvt_pk_bf16_f32 v251, v38, v39
	s_nop 1
	v_permlane16_swap_b32 v248, v250
	v_permlane16_swap_b32 v249, v251
	global_store_dwordx4 v222, v[248:251], s[14:15] offset:256
	s_waitcnt vmcnt(15)
	v_permlane16_swap_b32 v180, v182
	v_permlane16_swap_b32 v181, v183
	v_lshlrev_b32_e32 v204, 16, v180
	v_and_b32_e32 v205, 0xffff0000, v180
	v_lshlrev_b32_e32 v206, 16, v181
	v_and_b32_e32 v207, 0xffff0000, v181
	v_pk_mul_f32 v[32:33], v[32:33], v[204:205]
	v_pk_mul_f32 v[34:35], v[34:35], v[206:207]
	v_lshlrev_b32_e32 v204, 16, v182
	v_and_b32_e32 v205, 0xffff0000, v182
	v_lshlrev_b32_e32 v206, 16, v183
	v_and_b32_e32 v207, 0xffff0000, v183
	v_pk_mul_f32 v[28:29], v[28:29], v[204:205]
	v_pk_mul_f32 v[30:31], v[30:31], v[206:207]
	v_cvt_pk_bf16_f32 v226, v32, v33
	v_cvt_pk_bf16_f32 v227, v34, v35
	v_cvt_pk_bf16_f32 v228, v28, v29
	v_cvt_pk_bf16_f32 v229, v30, v31
	s_nop 1
	v_permlane16_swap_b32 v226, v228
	v_permlane16_swap_b32 v227, v229
	global_store_dwordx4 v223, v[226:229], s[14:15] offset:0
	s_waitcnt vmcnt(15)
	v_permlane16_swap_b32 v184, v186
	v_permlane16_swap_b32 v185, v187
	v_lshlrev_b32_e32 v204, 16, v184
	v_and_b32_e32 v205, 0xffff0000, v184
	v_lshlrev_b32_e32 v206, 16, v185
	v_and_b32_e32 v207, 0xffff0000, v185
	v_pk_mul_f32 v[24:25], v[24:25], v[204:205]
	v_pk_mul_f32 v[26:27], v[26:27], v[206:207]
	v_lshlrev_b32_e32 v204, 16, v186
	v_and_b32_e32 v205, 0xffff0000, v186
	v_lshlrev_b32_e32 v206, 16, v187
	v_and_b32_e32 v207, 0xffff0000, v187
	v_pk_mul_f32 v[20:21], v[20:21], v[204:205]
	v_pk_mul_f32 v[22:23], v[22:23], v[206:207]
	v_cvt_pk_bf16_f32 v230, v24, v25
	v_cvt_pk_bf16_f32 v231, v26, v27
	v_cvt_pk_bf16_f32 v232, v20, v21
	v_cvt_pk_bf16_f32 v233, v22, v23
	s_nop 1
	v_permlane16_swap_b32 v230, v232
	v_permlane16_swap_b32 v231, v233
	global_store_dwordx4 v223, v[230:233], s[14:15] offset:256
	s_waitcnt vmcnt(15)
	v_permlane16_swap_b32 v188, v190
	v_permlane16_swap_b32 v189, v191
	v_lshlrev_b32_e32 v204, 16, v188
	v_and_b32_e32 v205, 0xffff0000, v188
	v_lshlrev_b32_e32 v206, 16, v189
	v_and_b32_e32 v207, 0xffff0000, v189
	v_pk_mul_f32 v[16:17], v[16:17], v[204:205]
	v_pk_mul_f32 v[18:19], v[18:19], v[206:207]
	v_lshlrev_b32_e32 v204, 16, v190
	v_and_b32_e32 v205, 0xffff0000, v190
	v_lshlrev_b32_e32 v206, 16, v191
	v_and_b32_e32 v207, 0xffff0000, v191
	v_pk_mul_f32 v[12:13], v[12:13], v[204:205]
	v_pk_mul_f32 v[14:15], v[14:15], v[206:207]
	v_cvt_pk_bf16_f32 v244, v16, v17
	v_cvt_pk_bf16_f32 v245, v18, v19
	v_cvt_pk_bf16_f32 v246, v12, v13
	v_cvt_pk_bf16_f32 v247, v14, v15
	s_nop 1
	v_permlane16_swap_b32 v244, v246
	v_permlane16_swap_b32 v245, v247
	global_store_dwordx4 v224, v[244:247], s[14:15] offset:0
	s_waitcnt vmcnt(15)
	v_permlane16_swap_b32 v192, v194
	v_permlane16_swap_b32 v193, v195
	v_lshlrev_b32_e32 v204, 16, v192
	v_and_b32_e32 v205, 0xffff0000, v192
	v_lshlrev_b32_e32 v206, 16, v193
	v_and_b32_e32 v207, 0xffff0000, v193
	v_pk_mul_f32 v[8:9], v[8:9], v[204:205]
	v_pk_mul_f32 v[10:11], v[10:11], v[206:207]
	v_lshlrev_b32_e32 v204, 16, v194
	v_and_b32_e32 v205, 0xffff0000, v194
	v_lshlrev_b32_e32 v206, 16, v195
	v_and_b32_e32 v207, 0xffff0000, v195
	v_pk_mul_f32 v[4:5], v[4:5], v[204:205]
	v_pk_mul_f32 v[6:7], v[6:7], v[206:207]
	v_cvt_pk_bf16_f32 v248, v8, v9
	v_cvt_pk_bf16_f32 v249, v10, v11
	v_cvt_pk_bf16_f32 v250, v4, v5
	v_cvt_pk_bf16_f32 v251, v6, v7
	s_nop 1
	v_permlane16_swap_b32 v248, v250
	v_permlane16_swap_b32 v249, v251
	global_store_dwordx4 v224, v[248:251], s[14:15] offset:256
	s_branch .Lp5_done
.Lp5_full_seg1:
	v_mov_b32_e32 v217, v1
	v_add_u32_e32 v218, 0x10000, v1
	v_add_u32_e32 v219, 0x20000, v1
	v_add_u32_e32 v220, 0x30000, v1
	v_add_u32_e32 v221, 0x80000, v1
	v_add_u32_e32 v222, 0x90000, v1
	v_add_u32_e32 v223, 0xa0000, v1
	v_add_u32_e32 v224, 0xb0000, v1
	global_load_dwordx4 v[132:135], v217, s[26:27] offset:0
	global_load_dwordx4 v[136:139], v217, s[14:15] offset:0
	global_load_dwordx4 v[140:143], v217, s[26:27] offset:256
	global_load_dwordx4 v[144:147], v217, s[14:15] offset:256
	global_load_dwordx4 v[148:151], v218, s[26:27] offset:0
	global_load_dwordx4 v[152:155], v218, s[14:15] offset:0
	global_load_dwordx4 v[156:159], v218, s[26:27] offset:256
	global_load_dwordx4 v[160:163], v218, s[14:15] offset:256
	global_load_dwordx4 v[164:167], v219, s[26:27] offset:0
	global_load_dwordx4 v[168:171], v219, s[14:15] offset:0
	global_load_dwordx4 v[172:175], v219, s[26:27] offset:256
	global_load_dwordx4 v[176:179], v219, s[14:15] offset:256
	global_load_dwordx4 v[180:183], v220, s[26:27] offset:0
	global_load_dwordx4 v[184:187], v220, s[14:15] offset:0
	global_load_dwordx4 v[188:191], v220, s[26:27] offset:256
	global_load_dwordx4 v[192:195], v220, s[14:15] offset:256
	s_waitcnt vmcnt(14)
	v_permlane16_swap_b32 v132, v134
	v_permlane16_swap_b32 v133, v135
	v_permlane16_swap_b32 v136, v138
	v_permlane16_swap_b32 v137, v139
	v_lshlrev_b32_e32 v204, 16, v132
	v_and_b32_e32 v205, 0xffff0000, v132
	v_lshlrev_b32_e32 v206, 16, v133
	v_and_b32_e32 v207, 0xffff0000, v133
	v_pk_mul_f32 v[128:129], v[128:129], v[204:205]
	v_pk_mul_f32 v[130:131], v[130:131], v[206:207]
	v_lshlrev_b32_e32 v204, 16, v134
	v_and_b32_e32 v205, 0xffff0000, v134
	v_lshlrev_b32_e32 v206, 16, v135
	v_and_b32_e32 v207, 0xffff0000, v135
	v_pk_mul_f32 v[124:125], v[124:125], v[204:205]
	v_pk_mul_f32 v[126:127], v[126:127], v[206:207]
	v_lshlrev_b32_e32 v204, 16, v136
	v_and_b32_e32 v205, 0xffff0000, v136
	v_lshlrev_b32_e32 v206, 16, v137
	v_and_b32_e32 v207, 0xffff0000, v137
	v_pk_add_f32 v[128:129], v[128:129], v[204:205]
	v_pk_add_f32 v[130:131], v[130:131], v[206:207]
	v_lshlrev_b32_e32 v204, 16, v138
	v_and_b32_e32 v205, 0xffff0000, v138
	v_lshlrev_b32_e32 v206, 16, v139
	v_and_b32_e32 v207, 0xffff0000, v139
	v_pk_add_f32 v[124:125], v[124:125], v[204:205]
	v_pk_add_f32 v[126:127], v[126:127], v[206:207]
	v_cvt_pk_bf16_f32 v226, v128, v129
	v_cvt_pk_bf16_f32 v227, v130, v131
	v_cvt_pk_bf16_f32 v228, v124, v125
	v_cvt_pk_bf16_f32 v229, v126, v127
	s_nop 1
	v_permlane16_swap_b32 v226, v228
	v_permlane16_swap_b32 v227, v229
	global_store_dwordx4 v217, v[226:229], s[14:15] offset:0
	global_load_dwordx4 v[132:135], v221, s[26:27] offset:0
	global_load_dwordx4 v[136:139], v221, s[14:15] offset:0
	s_waitcnt vmcnt(15)
	v_permlane16_swap_b32 v140, v142
	v_permlane16_swap_b32 v141, v143
	v_permlane16_swap_b32 v144, v146
	v_permlane16_swap_b32 v145, v147
	v_lshlrev_b32_e32 v204, 16, v140
	v_and_b32_e32 v205, 0xffff0000, v140
	v_lshlrev_b32_e32 v206, 16, v141
	v_and_b32_e32 v207, 0xffff0000, v141
	v_pk_mul_f32 v[112:113], v[112:113], v[204:205]
	v_pk_mul_f32 v[114:115], v[114:115], v[206:207]
	v_lshlrev_b32_e32 v204, 16, v142
	v_and_b32_e32 v205, 0xffff0000, v142
	v_lshlrev_b32_e32 v206, 16, v143
	v_and_b32_e32 v207, 0xffff0000, v143
	v_pk_mul_f32 v[108:109], v[108:109], v[204:205]
	v_pk_mul_f32 v[110:111], v[110:111], v[206:207]
	v_lshlrev_b32_e32 v204, 16, v144
	v_and_b32_e32 v205, 0xffff0000, v144
	v_lshlrev_b32_e32 v206, 16, v145
	v_and_b32_e32 v207, 0xffff0000, v145
	v_pk_add_f32 v[112:113], v[112:113], v[204:205]
	v_pk_add_f32 v[114:115], v[114:115], v[206:207]
	v_lshlrev_b32_e32 v204, 16, v146
	v_and_b32_e32 v205, 0xffff0000, v146
	v_lshlrev_b32_e32 v206, 16, v147
	v_and_b32_e32 v207, 0xffff0000, v147
	v_pk_add_f32 v[108:109], v[108:109], v[204:205]
	v_pk_add_f32 v[110:111], v[110:111], v[206:207]
	v_cvt_pk_bf16_f32 v230, v112, v113
	v_cvt_pk_bf16_f32 v231, v114, v115
	v_cvt_pk_bf16_f32 v232, v108, v109
	v_cvt_pk_bf16_f32 v233, v110, v111
	s_nop 1
	v_permlane16_swap_b32 v230, v232
	v_permlane16_swap_b32 v231, v233
	global_store_dwordx4 v217, v[230:233], s[14:15] offset:256
	global_load_dwordx4 v[140:143], v221, s[26:27] offset:256
	global_load_dwordx4 v[144:147], v221, s[14:15] offset:256
	s_waitcnt vmcnt(16)
	v_permlane16_swap_b32 v148, v150
	v_permlane16_swap_b32 v149, v151
	v_permlane16_swap_b32 v152, v154
	v_permlane16_swap_b32 v153, v155
	v_lshlrev_b32_e32 v204, 16, v148
	v_and_b32_e32 v205, 0xffff0000, v148
	v_lshlrev_b32_e32 v206, 16, v149
	v_and_b32_e32 v207, 0xffff0000, v149
	v_pk_mul_f32 v[120:121], v[120:121], v[204:205]
	v_pk_mul_f32 v[122:123], v[122:123], v[206:207]
	v_lshlrev_b32_e32 v204, 16, v150
	v_and_b32_e32 v205, 0xffff0000, v150
	v_lshlrev_b32_e32 v206, 16, v151
	v_and_b32_e32 v207, 0xffff0000, v151
	v_pk_mul_f32 v[116:117], v[116:117], v[204:205]
	v_pk_mul_f32 v[118:119], v[118:119], v[206:207]
	v_lshlrev_b32_e32 v204, 16, v152
	v_and_b32_e32 v205, 0xffff0000, v152
	v_lshlrev_b32_e32 v206, 16, v153
	v_and_b32_e32 v207, 0xffff0000, v153
	v_pk_add_f32 v[120:121], v[120:121], v[204:205]
	v_pk_add_f32 v[122:123], v[122:123], v[206:207]
	v_lshlrev_b32_e32 v204, 16, v154
	v_and_b32_e32 v205, 0xffff0000, v154
	v_lshlrev_b32_e32 v206, 16, v155
	v_and_b32_e32 v207, 0xffff0000, v155
	v_pk_add_f32 v[116:117], v[116:117], v[204:205]
	v_pk_add_f32 v[118:119], v[118:119], v[206:207]
	v_cvt_pk_bf16_f32 v244, v120, v121
	v_cvt_pk_bf16_f32 v245, v122, v123
	v_cvt_pk_bf16_f32 v246, v116, v117
	v_cvt_pk_bf16_f32 v247, v118, v119
	s_nop 1
	v_permlane16_swap_b32 v244, v246
	v_permlane16_swap_b32 v245, v247
	global_store_dwordx4 v218, v[244:247], s[14:15] offset:0
	global_load_dwordx4 v[148:151], v222, s[26:27] offset:0
	global_load_dwordx4 v[152:155], v222, s[14:15] offset:0
	s_waitcnt vmcnt(17)
	v_permlane16_swap_b32 v156, v158
	v_permlane16_swap_b32 v157, v159
	v_permlane16_swap_b32 v160, v162
	v_permlane16_swap_b32 v161, v163
	v_lshlrev_b32_e32 v204, 16, v156
	v_and_b32_e32 v205, 0xffff0000, v156
	v_lshlrev_b32_e32 v206, 16, v157
	v_and_b32_e32 v207, 0xffff0000, v157
	v_pk_mul_f32 v[96:97], v[96:97], v[204:205]
	v_pk_mul_f32 v[98:99], v[98:99], v[206:207]
	v_lshlrev_b32_e32 v204, 16, v158
	v_and_b32_e32 v205, 0xffff0000, v158
	v_lshlrev_b32_e32 v206, 16, v159
	v_and_b32_e32 v207, 0xffff0000, v159
	v_pk_mul_f32 v[92:93], v[92:93], v[204:205]
	v_pk_mul_f32 v[94:95], v[94:95], v[206:207]
	v_lshlrev_b32_e32 v204, 16, v160
	v_and_b32_e32 v205, 0xffff0000, v160
	v_lshlrev_b32_e32 v206, 16, v161
	v_and_b32_e32 v207, 0xffff0000, v161
	v_pk_add_f32 v[96:97], v[96:97], v[204:205]
	v_pk_add_f32 v[98:99], v[98:99], v[206:207]
	v_lshlrev_b32_e32 v204, 16, v162
	v_and_b32_e32 v205, 0xffff0000, v162
	v_lshlrev_b32_e32 v206, 16, v163
	v_and_b32_e32 v207, 0xffff0000, v163
	v_pk_add_f32 v[92:93], v[92:93], v[204:205]
	v_pk_add_f32 v[94:95], v[94:95], v[206:207]
	v_cvt_pk_bf16_f32 v248, v96, v97
	v_cvt_pk_bf16_f32 v249, v98, v99
	v_cvt_pk_bf16_f32 v250, v92, v93
	v_cvt_pk_bf16_f32 v251, v94, v95
	s_nop 1
	v_permlane16_swap_b32 v248, v250
	v_permlane16_swap_b32 v249, v251
	global_store_dwordx4 v218, v[248:251], s[14:15] offset:256
	global_load_dwordx4 v[156:159], v222, s[26:27] offset:256
	global_load_dwordx4 v[160:163], v222, s[14:15] offset:256
	s_waitcnt vmcnt(18)
	v_permlane16_swap_b32 v164, v166
	v_permlane16_swap_b32 v165, v167
	v_permlane16_swap_b32 v168, v170
	v_permlane16_swap_b32 v169, v171
	v_lshlrev_b32_e32 v204, 16, v164
	v_and_b32_e32 v205, 0xffff0000, v164
	v_lshlrev_b32_e32 v206, 16, v165
	v_and_b32_e32 v207, 0xffff0000, v165
	v_pk_mul_f32 v[104:105], v[104:105], v[204:205]
	v_pk_mul_f32 v[106:107], v[106:107], v[206:207]
	v_lshlrev_b32_e32 v204, 16, v166
	v_and_b32_e32 v205, 0xffff0000, v166
	v_lshlrev_b32_e32 v206, 16, v167
	v_and_b32_e32 v207, 0xffff0000, v167
	v_pk_mul_f32 v[100:101], v[100:101], v[204:205]
	v_pk_mul_f32 v[102:103], v[102:103], v[206:207]
	v_lshlrev_b32_e32 v204, 16, v168
	v_and_b32_e32 v205, 0xffff0000, v168
	v_lshlrev_b32_e32 v206, 16, v169
	v_and_b32_e32 v207, 0xffff0000, v169
	v_pk_add_f32 v[104:105], v[104:105], v[204:205]
	v_pk_add_f32 v[106:107], v[106:107], v[206:207]
	v_lshlrev_b32_e32 v204, 16, v170
	v_and_b32_e32 v205, 0xffff0000, v170
	v_lshlrev_b32_e32 v206, 16, v171
	v_and_b32_e32 v207, 0xffff0000, v171
	v_pk_add_f32 v[100:101], v[100:101], v[204:205]
	v_pk_add_f32 v[102:103], v[102:103], v[206:207]
	v_cvt_pk_bf16_f32 v226, v104, v105
	v_cvt_pk_bf16_f32 v227, v106, v107
	v_cvt_pk_bf16_f32 v228, v100, v101
	v_cvt_pk_bf16_f32 v229, v102, v103
	s_nop 1
	v_permlane16_swap_b32 v226, v228
	v_permlane16_swap_b32 v227, v229
	global_store_dwordx4 v219, v[226:229], s[14:15] offset:0
	global_load_dwordx4 v[164:167], v223, s[26:27] offset:0
	global_load_dwordx4 v[168:171], v223, s[14:15] offset:0
	s_waitcnt vmcnt(19)
	v_permlane16_swap_b32 v172, v174
	v_permlane16_swap_b32 v173, v175
	v_permlane16_swap_b32 v176, v178
	v_permlane16_swap_b32 v177, v179
	v_lshlrev_b32_e32 v204, 16, v172
	v_and_b32_e32 v205, 0xffff0000, v172
	v_lshlrev_b32_e32 v206, 16, v173
	v_and_b32_e32 v207, 0xffff0000, v173
	v_pk_mul_f32 v[80:81], v[80:81], v[204:205]
	v_pk_mul_f32 v[82:83], v[82:83], v[206:207]
	v_lshlrev_b32_e32 v204, 16, v174
	v_and_b32_e32 v205, 0xffff0000, v174
	v_lshlrev_b32_e32 v206, 16, v175
	v_and_b32_e32 v207, 0xffff0000, v175
	v_pk_mul_f32 v[76:77], v[76:77], v[204:205]
	v_pk_mul_f32 v[78:79], v[78:79], v[206:207]
	v_lshlrev_b32_e32 v204, 16, v176
	v_and_b32_e32 v205, 0xffff0000, v176
	v_lshlrev_b32_e32 v206, 16, v177
	v_and_b32_e32 v207, 0xffff0000, v177
	v_pk_add_f32 v[80:81], v[80:81], v[204:205]
	v_pk_add_f32 v[82:83], v[82:83], v[206:207]
	v_lshlrev_b32_e32 v204, 16, v178
	v_and_b32_e32 v205, 0xffff0000, v178
	v_lshlrev_b32_e32 v206, 16, v179
	v_and_b32_e32 v207, 0xffff0000, v179
	v_pk_add_f32 v[76:77], v[76:77], v[204:205]
	v_pk_add_f32 v[78:79], v[78:79], v[206:207]
	v_cvt_pk_bf16_f32 v230, v80, v81
	v_cvt_pk_bf16_f32 v231, v82, v83
	v_cvt_pk_bf16_f32 v232, v76, v77
	v_cvt_pk_bf16_f32 v233, v78, v79
	s_nop 1
	v_permlane16_swap_b32 v230, v232
	v_permlane16_swap_b32 v231, v233
	global_store_dwordx4 v219, v[230:233], s[14:15] offset:256
	global_load_dwordx4 v[172:175], v223, s[26:27] offset:256
	global_load_dwordx4 v[176:179], v223, s[14:15] offset:256
	s_waitcnt vmcnt(20)
	v_permlane16_swap_b32 v180, v182
	v_permlane16_swap_b32 v181, v183
	v_permlane16_swap_b32 v184, v186
	v_permlane16_swap_b32 v185, v187
	v_lshlrev_b32_e32 v204, 16, v180
	v_and_b32_e32 v205, 0xffff0000, v180
	v_lshlrev_b32_e32 v206, 16, v181
	v_and_b32_e32 v207, 0xffff0000, v181
	v_pk_mul_f32 v[88:89], v[88:89], v[204:205]
	v_pk_mul_f32 v[90:91], v[90:91], v[206:207]
	v_lshlrev_b32_e32 v204, 16, v182
	v_and_b32_e32 v205, 0xffff0000, v182
	v_lshlrev_b32_e32 v206, 16, v183
	v_and_b32_e32 v207, 0xffff0000, v183
	v_pk_mul_f32 v[84:85], v[84:85], v[204:205]
	v_pk_mul_f32 v[86:87], v[86:87], v[206:207]
	v_lshlrev_b32_e32 v204, 16, v184
	v_and_b32_e32 v205, 0xffff0000, v184
	v_lshlrev_b32_e32 v206, 16, v185
	v_and_b32_e32 v207, 0xffff0000, v185
	v_pk_add_f32 v[88:89], v[88:89], v[204:205]
	v_pk_add_f32 v[90:91], v[90:91], v[206:207]
	v_lshlrev_b32_e32 v204, 16, v186
	v_and_b32_e32 v205, 0xffff0000, v186
	v_lshlrev_b32_e32 v206, 16, v187
	v_and_b32_e32 v207, 0xffff0000, v187
	v_pk_add_f32 v[84:85], v[84:85], v[204:205]
	v_pk_add_f32 v[86:87], v[86:87], v[206:207]
	v_cvt_pk_bf16_f32 v244, v88, v89
	v_cvt_pk_bf16_f32 v245, v90, v91
	v_cvt_pk_bf16_f32 v246, v84, v85
	v_cvt_pk_bf16_f32 v247, v86, v87
	s_nop 1
	v_permlane16_swap_b32 v244, v246
	v_permlane16_swap_b32 v245, v247
	global_store_dwordx4 v220, v[244:247], s[14:15] offset:0
	global_load_dwordx4 v[180:183], v224, s[26:27] offset:0
	global_load_dwordx4 v[184:187], v224, s[14:15] offset:0
	s_waitcnt vmcnt(21)
	v_permlane16_swap_b32 v188, v190
	v_permlane16_swap_b32 v189, v191
	v_permlane16_swap_b32 v192, v194
	v_permlane16_swap_b32 v193, v195
	v_lshlrev_b32_e32 v204, 16, v188
	v_and_b32_e32 v205, 0xffff0000, v188
	v_lshlrev_b32_e32 v206, 16, v189
	v_and_b32_e32 v207, 0xffff0000, v189
	v_pk_mul_f32 v[72:73], v[72:73], v[204:205]
	v_pk_mul_f32 v[74:75], v[74:75], v[206:207]
	v_lshlrev_b32_e32 v204, 16, v190
	v_and_b32_e32 v205, 0xffff0000, v190
	v_lshlrev_b32_e32 v206, 16, v191
	v_and_b32_e32 v207, 0xffff0000, v191
	v_pk_mul_f32 v[68:69], v[68:69], v[204:205]
	v_pk_mul_f32 v[70:71], v[70:71], v[206:207]
	v_lshlrev_b32_e32 v204, 16, v192
	v_and_b32_e32 v205, 0xffff0000, v192
	v_lshlrev_b32_e32 v206, 16, v193
	v_and_b32_e32 v207, 0xffff0000, v193
	v_pk_add_f32 v[72:73], v[72:73], v[204:205]
	v_pk_add_f32 v[74:75], v[74:75], v[206:207]
	v_lshlrev_b32_e32 v204, 16, v194
	v_and_b32_e32 v205, 0xffff0000, v194
	v_lshlrev_b32_e32 v206, 16, v195
	v_and_b32_e32 v207, 0xffff0000, v195
	v_pk_add_f32 v[68:69], v[68:69], v[204:205]
	v_pk_add_f32 v[70:71], v[70:71], v[206:207]
	v_cvt_pk_bf16_f32 v248, v72, v73
	v_cvt_pk_bf16_f32 v249, v74, v75
	v_cvt_pk_bf16_f32 v250, v68, v69
	v_cvt_pk_bf16_f32 v251, v70, v71
	s_nop 1
	v_permlane16_swap_b32 v248, v250
	v_permlane16_swap_b32 v249, v251
	global_store_dwordx4 v220, v[248:251], s[14:15] offset:256
	global_load_dwordx4 v[188:191], v224, s[26:27] offset:256
	global_load_dwordx4 v[192:195], v224, s[14:15] offset:256
	s_waitcnt vmcnt(21)
	v_permlane16_swap_b32 v132, v134
	v_permlane16_swap_b32 v133, v135
	v_permlane16_swap_b32 v136, v138
	v_permlane16_swap_b32 v137, v139
	v_lshlrev_b32_e32 v204, 16, v132
	v_and_b32_e32 v205, 0xffff0000, v132
	v_lshlrev_b32_e32 v206, 16, v133
	v_and_b32_e32 v207, 0xffff0000, v133
	v_pk_mul_f32 v[64:65], v[64:65], v[204:205]
	v_pk_mul_f32 v[66:67], v[66:67], v[206:207]
	v_lshlrev_b32_e32 v204, 16, v134
	v_and_b32_e32 v205, 0xffff0000, v134
	v_lshlrev_b32_e32 v206, 16, v135
	v_and_b32_e32 v207, 0xffff0000, v135
	v_pk_mul_f32 v[60:61], v[60:61], v[204:205]
	v_pk_mul_f32 v[62:63], v[62:63], v[206:207]
	v_lshlrev_b32_e32 v204, 16, v136
	v_and_b32_e32 v205, 0xffff0000, v136
	v_lshlrev_b32_e32 v206, 16, v137
	v_and_b32_e32 v207, 0xffff0000, v137
	v_pk_add_f32 v[64:65], v[64:65], v[204:205]
	v_pk_add_f32 v[66:67], v[66:67], v[206:207]
	v_lshlrev_b32_e32 v204, 16, v138
	v_and_b32_e32 v205, 0xffff0000, v138
	v_lshlrev_b32_e32 v206, 16, v139
	v_and_b32_e32 v207, 0xffff0000, v139
	v_pk_add_f32 v[60:61], v[60:61], v[204:205]
	v_pk_add_f32 v[62:63], v[62:63], v[206:207]
	v_cvt_pk_bf16_f32 v226, v64, v65
	v_cvt_pk_bf16_f32 v227, v66, v67
	v_cvt_pk_bf16_f32 v228, v60, v61
	v_cvt_pk_bf16_f32 v229, v62, v63
	s_nop 1
	v_permlane16_swap_b32 v226, v228
	v_permlane16_swap_b32 v227, v229
	global_store_dwordx4 v221, v[226:229], s[14:15] offset:0
	s_waitcnt vmcnt(19)
	v_permlane16_swap_b32 v140, v142
	v_permlane16_swap_b32 v141, v143
	v_permlane16_swap_b32 v144, v146
	v_permlane16_swap_b32 v145, v147
	v_lshlrev_b32_e32 v204, 16, v140
	v_and_b32_e32 v205, 0xffff0000, v140
	v_lshlrev_b32_e32 v206, 16, v141
	v_and_b32_e32 v207, 0xffff0000, v141
	v_pk_mul_f32 v[56:57], v[56:57], v[204:205]
	v_pk_mul_f32 v[58:59], v[58:59], v[206:207]
	v_lshlrev_b32_e32 v204, 16, v142
	v_and_b32_e32 v205, 0xffff0000, v142
	v_lshlrev_b32_e32 v206, 16, v143
	v_and_b32_e32 v207, 0xffff0000, v143
	v_pk_mul_f32 v[52:53], v[52:53], v[204:205]
	v_pk_mul_f32 v[54:55], v[54:55], v[206:207]
	v_lshlrev_b32_e32 v204, 16, v144
	v_and_b32_e32 v205, 0xffff0000, v144
	v_lshlrev_b32_e32 v206, 16, v145
	v_and_b32_e32 v207, 0xffff0000, v145
	v_pk_add_f32 v[56:57], v[56:57], v[204:205]
	v_pk_add_f32 v[58:59], v[58:59], v[206:207]
	v_lshlrev_b32_e32 v204, 16, v146
	v_and_b32_e32 v205, 0xffff0000, v146
	v_lshlrev_b32_e32 v206, 16, v147
	v_and_b32_e32 v207, 0xffff0000, v147
	v_pk_add_f32 v[52:53], v[52:53], v[204:205]
	v_pk_add_f32 v[54:55], v[54:55], v[206:207]
	v_cvt_pk_bf16_f32 v230, v56, v57
	v_cvt_pk_bf16_f32 v231, v58, v59
	v_cvt_pk_bf16_f32 v232, v52, v53
	v_cvt_pk_bf16_f32 v233, v54, v55
	s_nop 1
	v_permlane16_swap_b32 v230, v232
	v_permlane16_swap_b32 v231, v233
	global_store_dwordx4 v221, v[230:233], s[14:15] offset:256
	s_waitcnt vmcnt(17)
	v_permlane16_swap_b32 v148, v150
	v_permlane16_swap_b32 v149, v151
	v_permlane16_swap_b32 v152, v154
	v_permlane16_swap_b32 v153, v155
	v_lshlrev_b32_e32 v204, 16, v148
	v_and_b32_e32 v205, 0xffff0000, v148
	v_lshlrev_b32_e32 v206, 16, v149
	v_and_b32_e32 v207, 0xffff0000, v149
	v_pk_mul_f32 v[48:49], v[48:49], v[204:205]
	v_pk_mul_f32 v[50:51], v[50:51], v[206:207]
	v_lshlrev_b32_e32 v204, 16, v150
	v_and_b32_e32 v205, 0xffff0000, v150
	v_lshlrev_b32_e32 v206, 16, v151
	v_and_b32_e32 v207, 0xffff0000, v151
	v_pk_mul_f32 v[44:45], v[44:45], v[204:205]
	v_pk_mul_f32 v[46:47], v[46:47], v[206:207]
	v_lshlrev_b32_e32 v204, 16, v152
	v_and_b32_e32 v205, 0xffff0000, v152
	v_lshlrev_b32_e32 v206, 16, v153
	v_and_b32_e32 v207, 0xffff0000, v153
	v_pk_add_f32 v[48:49], v[48:49], v[204:205]
	v_pk_add_f32 v[50:51], v[50:51], v[206:207]
	v_lshlrev_b32_e32 v204, 16, v154
	v_and_b32_e32 v205, 0xffff0000, v154
	v_lshlrev_b32_e32 v206, 16, v155
	v_and_b32_e32 v207, 0xffff0000, v155
	v_pk_add_f32 v[44:45], v[44:45], v[204:205]
	v_pk_add_f32 v[46:47], v[46:47], v[206:207]
	v_cvt_pk_bf16_f32 v244, v48, v49
	v_cvt_pk_bf16_f32 v245, v50, v51
	v_cvt_pk_bf16_f32 v246, v44, v45
	v_cvt_pk_bf16_f32 v247, v46, v47
	s_nop 1
	v_permlane16_swap_b32 v244, v246
	v_permlane16_swap_b32 v245, v247
	global_store_dwordx4 v222, v[244:247], s[14:15] offset:0
	s_waitcnt vmcnt(15)
	v_permlane16_swap_b32 v156, v158
	v_permlane16_swap_b32 v157, v159
	v_permlane16_swap_b32 v160, v162
	v_permlane16_swap_b32 v161, v163
	v_lshlrev_b32_e32 v204, 16, v156
	v_and_b32_e32 v205, 0xffff0000, v156
	v_lshlrev_b32_e32 v206, 16, v157
	v_and_b32_e32 v207, 0xffff0000, v157
	v_pk_mul_f32 v[40:41], v[40:41], v[204:205]
	v_pk_mul_f32 v[42:43], v[42:43], v[206:207]
	v_lshlrev_b32_e32 v204, 16, v158
	v_and_b32_e32 v205, 0xffff0000, v158
	v_lshlrev_b32_e32 v206, 16, v159
	v_and_b32_e32 v207, 0xffff0000, v159
	v_pk_mul_f32 v[36:37], v[36:37], v[204:205]
	v_pk_mul_f32 v[38:39], v[38:39], v[206:207]
	v_lshlrev_b32_e32 v204, 16, v160
	v_and_b32_e32 v205, 0xffff0000, v160
	v_lshlrev_b32_e32 v206, 16, v161
	v_and_b32_e32 v207, 0xffff0000, v161
	v_pk_add_f32 v[40:41], v[40:41], v[204:205]
	v_pk_add_f32 v[42:43], v[42:43], v[206:207]
	v_lshlrev_b32_e32 v204, 16, v162
	v_and_b32_e32 v205, 0xffff0000, v162
	v_lshlrev_b32_e32 v206, 16, v163
	v_and_b32_e32 v207, 0xffff0000, v163
	v_pk_add_f32 v[36:37], v[36:37], v[204:205]
	v_pk_add_f32 v[38:39], v[38:39], v[206:207]
	v_cvt_pk_bf16_f32 v248, v40, v41
	v_cvt_pk_bf16_f32 v249, v42, v43
	v_cvt_pk_bf16_f32 v250, v36, v37
	v_cvt_pk_bf16_f32 v251, v38, v39
	s_nop 1
	v_permlane16_swap_b32 v248, v250
	v_permlane16_swap_b32 v249, v251
	global_store_dwordx4 v222, v[248:251], s[14:15] offset:256
	s_waitcnt vmcnt(13)
	v_permlane16_swap_b32 v164, v166
	v_permlane16_swap_b32 v165, v167
	v_permlane16_swap_b32 v168, v170
	v_permlane16_swap_b32 v169, v171
	v_lshlrev_b32_e32 v204, 16, v164
	v_and_b32_e32 v205, 0xffff0000, v164
	v_lshlrev_b32_e32 v206, 16, v165
	v_and_b32_e32 v207, 0xffff0000, v165
	v_pk_mul_f32 v[32:33], v[32:33], v[204:205]
	v_pk_mul_f32 v[34:35], v[34:35], v[206:207]
	v_lshlrev_b32_e32 v204, 16, v166
	v_and_b32_e32 v205, 0xffff0000, v166
	v_lshlrev_b32_e32 v206, 16, v167
	v_and_b32_e32 v207, 0xffff0000, v167
	v_pk_mul_f32 v[28:29], v[28:29], v[204:205]
	v_pk_mul_f32 v[30:31], v[30:31], v[206:207]
	v_lshlrev_b32_e32 v204, 16, v168
	v_and_b32_e32 v205, 0xffff0000, v168
	v_lshlrev_b32_e32 v206, 16, v169
	v_and_b32_e32 v207, 0xffff0000, v169
	v_pk_add_f32 v[32:33], v[32:33], v[204:205]
	v_pk_add_f32 v[34:35], v[34:35], v[206:207]
	v_lshlrev_b32_e32 v204, 16, v170
	v_and_b32_e32 v205, 0xffff0000, v170
	v_lshlrev_b32_e32 v206, 16, v171
	v_and_b32_e32 v207, 0xffff0000, v171
	v_pk_add_f32 v[28:29], v[28:29], v[204:205]
	v_pk_add_f32 v[30:31], v[30:31], v[206:207]
	v_cvt_pk_bf16_f32 v226, v32, v33
	v_cvt_pk_bf16_f32 v227, v34, v35
	v_cvt_pk_bf16_f32 v228, v28, v29
	v_cvt_pk_bf16_f32 v229, v30, v31
	s_nop 1
	v_permlane16_swap_b32 v226, v228
	v_permlane16_swap_b32 v227, v229
	global_store_dwordx4 v223, v[226:229], s[14:15] offset:0
	s_waitcnt vmcnt(11)
	v_permlane16_swap_b32 v172, v174
	v_permlane16_swap_b32 v173, v175
	v_permlane16_swap_b32 v176, v178
	v_permlane16_swap_b32 v177, v179
	v_lshlrev_b32_e32 v204, 16, v172
	v_and_b32_e32 v205, 0xffff0000, v172
	v_lshlrev_b32_e32 v206, 16, v173
	v_and_b32_e32 v207, 0xffff0000, v173
	v_pk_mul_f32 v[24:25], v[24:25], v[204:205]
	v_pk_mul_f32 v[26:27], v[26:27], v[206:207]
	v_lshlrev_b32_e32 v204, 16, v174
	v_and_b32_e32 v205, 0xffff0000, v174
	v_lshlrev_b32_e32 v206, 16, v175
	v_and_b32_e32 v207, 0xffff0000, v175
	v_pk_mul_f32 v[20:21], v[20:21], v[204:205]
	v_pk_mul_f32 v[22:23], v[22:23], v[206:207]
	v_lshlrev_b32_e32 v204, 16, v176
	v_and_b32_e32 v205, 0xffff0000, v176
	v_lshlrev_b32_e32 v206, 16, v177
	v_and_b32_e32 v207, 0xffff0000, v177
	v_pk_add_f32 v[24:25], v[24:25], v[204:205]
	v_pk_add_f32 v[26:27], v[26:27], v[206:207]
	v_lshlrev_b32_e32 v204, 16, v178
	v_and_b32_e32 v205, 0xffff0000, v178
	v_lshlrev_b32_e32 v206, 16, v179
	v_and_b32_e32 v207, 0xffff0000, v179
	v_pk_add_f32 v[20:21], v[20:21], v[204:205]
	v_pk_add_f32 v[22:23], v[22:23], v[206:207]
	v_cvt_pk_bf16_f32 v230, v24, v25
	v_cvt_pk_bf16_f32 v231, v26, v27
	v_cvt_pk_bf16_f32 v232, v20, v21
	v_cvt_pk_bf16_f32 v233, v22, v23
	s_nop 1
	v_permlane16_swap_b32 v230, v232
	v_permlane16_swap_b32 v231, v233
	global_store_dwordx4 v223, v[230:233], s[14:15] offset:256
	s_waitcnt vmcnt(9)
	v_permlane16_swap_b32 v180, v182
	v_permlane16_swap_b32 v181, v183
	v_permlane16_swap_b32 v184, v186
	v_permlane16_swap_b32 v185, v187
	v_lshlrev_b32_e32 v204, 16, v180
	v_and_b32_e32 v205, 0xffff0000, v180
	v_lshlrev_b32_e32 v206, 16, v181
	v_and_b32_e32 v207, 0xffff0000, v181
	v_pk_mul_f32 v[16:17], v[16:17], v[204:205]
	v_pk_mul_f32 v[18:19], v[18:19], v[206:207]
	v_lshlrev_b32_e32 v204, 16, v182
	v_and_b32_e32 v205, 0xffff0000, v182
	v_lshlrev_b32_e32 v206, 16, v183
	v_and_b32_e32 v207, 0xffff0000, v183
	v_pk_mul_f32 v[12:13], v[12:13], v[204:205]
	v_pk_mul_f32 v[14:15], v[14:15], v[206:207]
	v_lshlrev_b32_e32 v204, 16, v184
	v_and_b32_e32 v205, 0xffff0000, v184
	v_lshlrev_b32_e32 v206, 16, v185
	v_and_b32_e32 v207, 0xffff0000, v185
	v_pk_add_f32 v[16:17], v[16:17], v[204:205]
	v_pk_add_f32 v[18:19], v[18:19], v[206:207]
	v_lshlrev_b32_e32 v204, 16, v186
	v_and_b32_e32 v205, 0xffff0000, v186
	v_lshlrev_b32_e32 v206, 16, v187
	v_and_b32_e32 v207, 0xffff0000, v187
	v_pk_add_f32 v[12:13], v[12:13], v[204:205]
	v_pk_add_f32 v[14:15], v[14:15], v[206:207]
	v_cvt_pk_bf16_f32 v244, v16, v17
	v_cvt_pk_bf16_f32 v245, v18, v19
	v_cvt_pk_bf16_f32 v246, v12, v13
	v_cvt_pk_bf16_f32 v247, v14, v15
	s_nop 1
	v_permlane16_swap_b32 v244, v246
	v_permlane16_swap_b32 v245, v247
	global_store_dwordx4 v224, v[244:247], s[14:15] offset:0
	s_waitcnt vmcnt(7)
	v_permlane16_swap_b32 v188, v190
	v_permlane16_swap_b32 v189, v191
	v_permlane16_swap_b32 v192, v194
	v_permlane16_swap_b32 v193, v195
	v_lshlrev_b32_e32 v204, 16, v188
	v_and_b32_e32 v205, 0xffff0000, v188
	v_lshlrev_b32_e32 v206, 16, v189
	v_and_b32_e32 v207, 0xffff0000, v189
	v_pk_mul_f32 v[8:9], v[8:9], v[204:205]
	v_pk_mul_f32 v[10:11], v[10:11], v[206:207]
	v_lshlrev_b32_e32 v204, 16, v190
	v_and_b32_e32 v205, 0xffff0000, v190
	v_lshlrev_b32_e32 v206, 16, v191
	v_and_b32_e32 v207, 0xffff0000, v191
	v_pk_mul_f32 v[4:5], v[4:5], v[204:205]
	v_pk_mul_f32 v[6:7], v[6:7], v[206:207]
	v_lshlrev_b32_e32 v204, 16, v192
	v_and_b32_e32 v205, 0xffff0000, v192
	v_lshlrev_b32_e32 v206, 16, v193
	v_and_b32_e32 v207, 0xffff0000, v193
	v_pk_add_f32 v[8:9], v[8:9], v[204:205]
	v_pk_add_f32 v[10:11], v[10:11], v[206:207]
	v_lshlrev_b32_e32 v204, 16, v194
	v_and_b32_e32 v205, 0xffff0000, v194
	v_lshlrev_b32_e32 v206, 16, v195
	v_and_b32_e32 v207, 0xffff0000, v195
	v_pk_add_f32 v[4:5], v[4:5], v[204:205]
	v_pk_add_f32 v[6:7], v[6:7], v[206:207]
	v_cvt_pk_bf16_f32 v248, v8, v9
	v_cvt_pk_bf16_f32 v249, v10, v11
	v_cvt_pk_bf16_f32 v250, v4, v5
	v_cvt_pk_bf16_f32 v251, v6, v7
	s_nop 1
	v_permlane16_swap_b32 v248, v250
	v_permlane16_swap_b32 v249, v251
	global_store_dwordx4 v224, v[248:251], s[14:15] offset:256
	s_branch .Lp5_done
.Lp5_quart:
	s_cmp_eq_u32 s2, 0
	s_cbranch_scc0 .Lp5_quart_seg1
	v_mov_b32_e32 v217, v1
	v_add_u32_e32 v218, 0x10000, v1
	v_add_u32_e32 v219, 0x20000, v1
	v_add_u32_e32 v220, 0x30000, v1
	global_load_dwordx4 v[132:135], v217, s[26:27] offset:0
	global_load_dwordx4 v[136:139], v218, s[26:27] offset:0
	global_load_dwordx4 v[140:143], v219, s[26:27] offset:0
	global_load_dwordx4 v[144:147], v220, s[26:27] offset:0
	s_waitcnt vmcnt(3)
	v_permlane16_swap_b32 v132, v134
	v_permlane16_swap_b32 v133, v135
	v_lshlrev_b32_e32 v204, 16, v132
	v_and_b32_e32 v205, 0xffff0000, v132
	v_lshlrev_b32_e32 v206, 16, v133
	v_and_b32_e32 v207, 0xffff0000, v133
	v_pk_mul_f32 v[128:129], v[128:129], v[204:205]
	v_pk_mul_f32 v[130:131], v[130:131], v[206:207]
	v_lshlrev_b32_e32 v204, 16, v134
	v_and_b32_e32 v205, 0xffff0000, v134
	v_lshlrev_b32_e32 v206, 16, v135
	v_and_b32_e32 v207, 0xffff0000, v135
	v_pk_mul_f32 v[124:125], v[124:125], v[204:205]
	v_pk_mul_f32 v[126:127], v[126:127], v[206:207]
	v_cvt_pk_bf16_f32 v226, v128, v129
	v_cvt_pk_bf16_f32 v227, v130, v131
	v_cvt_pk_bf16_f32 v228, v124, v125
	v_cvt_pk_bf16_f32 v229, v126, v127
	s_nop 1
	v_permlane16_swap_b32 v226, v228
	v_permlane16_swap_b32 v227, v229
	global_store_dwordx4 v217, v[226:229], s[14:15] offset:0
	s_waitcnt vmcnt(3)
	v_permlane16_swap_b32 v136, v138
	v_permlane16_swap_b32 v137, v139
	v_lshlrev_b32_e32 v204, 16, v136
	v_and_b32_e32 v205, 0xffff0000, v136
	v_lshlrev_b32_e32 v206, 16, v137
	v_and_b32_e32 v207, 0xffff0000, v137
	v_pk_mul_f32 v[120:121], v[120:121], v[204:205]
	v_pk_mul_f32 v[122:123], v[122:123], v[206:207]
	v_lshlrev_b32_e32 v204, 16, v138
	v_and_b32_e32 v205, 0xffff0000, v138
	v_lshlrev_b32_e32 v206, 16, v139
	v_and_b32_e32 v207, 0xffff0000, v139
	v_pk_mul_f32 v[116:117], v[116:117], v[204:205]
	v_pk_mul_f32 v[118:119], v[118:119], v[206:207]
	v_cvt_pk_bf16_f32 v230, v120, v121
	v_cvt_pk_bf16_f32 v231, v122, v123
	v_cvt_pk_bf16_f32 v232, v116, v117
	v_cvt_pk_bf16_f32 v233, v118, v119
	s_nop 1
	v_permlane16_swap_b32 v230, v232
	v_permlane16_swap_b32 v231, v233
	global_store_dwordx4 v218, v[230:233], s[14:15] offset:0
	s_waitcnt vmcnt(3)
	v_permlane16_swap_b32 v140, v142
	v_permlane16_swap_b32 v141, v143
	v_lshlrev_b32_e32 v204, 16, v140
	v_and_b32_e32 v205, 0xffff0000, v140
	v_lshlrev_b32_e32 v206, 16, v141
	v_and_b32_e32 v207, 0xffff0000, v141
	v_pk_mul_f32 v[104:105], v[104:105], v[204:205]
	v_pk_mul_f32 v[106:107], v[106:107], v[206:207]
	v_lshlrev_b32_e32 v204, 16, v142
	v_and_b32_e32 v205, 0xffff0000, v142
	v_lshlrev_b32_e32 v206, 16, v143
	v_and_b32_e32 v207, 0xffff0000, v143
	v_pk_mul_f32 v[100:101], v[100:101], v[204:205]
	v_pk_mul_f32 v[102:103], v[102:103], v[206:207]
	v_cvt_pk_bf16_f32 v244, v104, v105
	v_cvt_pk_bf16_f32 v245, v106, v107
	v_cvt_pk_bf16_f32 v246, v100, v101
	v_cvt_pk_bf16_f32 v247, v102, v103
	s_nop 1
	v_permlane16_swap_b32 v244, v246
	v_permlane16_swap_b32 v245, v247
	global_store_dwordx4 v219, v[244:247], s[14:15] offset:0
	s_waitcnt vmcnt(3)
	v_permlane16_swap_b32 v144, v146
	v_permlane16_swap_b32 v145, v147
	v_lshlrev_b32_e32 v204, 16, v144
	v_and_b32_e32 v205, 0xffff0000, v144
	v_lshlrev_b32_e32 v206, 16, v145
	v_and_b32_e32 v207, 0xffff0000, v145
	v_pk_mul_f32 v[88:89], v[88:89], v[204:205]
	v_pk_mul_f32 v[90:91], v[90:91], v[206:207]
	v_lshlrev_b32_e32 v204, 16, v146
	v_and_b32_e32 v205, 0xffff0000, v146
	v_lshlrev_b32_e32 v206, 16, v147
	v_and_b32_e32 v207, 0xffff0000, v147
	v_pk_mul_f32 v[84:85], v[84:85], v[204:205]
	v_pk_mul_f32 v[86:87], v[86:87], v[206:207]
	v_cvt_pk_bf16_f32 v248, v88, v89
	v_cvt_pk_bf16_f32 v249, v90, v91
	v_cvt_pk_bf16_f32 v250, v84, v85
	v_cvt_pk_bf16_f32 v251, v86, v87
	s_nop 1
	v_permlane16_swap_b32 v248, v250
	v_permlane16_swap_b32 v249, v251
	global_store_dwordx4 v220, v[248:251], s[14:15] offset:0
	s_branch .Lp5_done
.Lp5_quart_seg1:
	v_mov_b32_e32 v217, v1
	v_add_u32_e32 v218, 0x10000, v1
	v_add_u32_e32 v219, 0x20000, v1
	v_add_u32_e32 v220, 0x30000, v1
	global_load_dwordx4 v[132:135], v217, s[26:27] offset:0
	global_load_dwordx4 v[136:139], v217, s[14:15] offset:0
	global_load_dwordx4 v[140:143], v218, s[26:27] offset:0
	global_load_dwordx4 v[144:147], v218, s[14:15] offset:0
	global_load_dwordx4 v[148:151], v219, s[26:27] offset:0
	global_load_dwordx4 v[152:155], v219, s[14:15] offset:0
	global_load_dwordx4 v[156:159], v220, s[26:27] offset:0
	global_load_dwordx4 v[160:163], v220, s[14:15] offset:0
	s_waitcnt vmcnt(6)
	v_permlane16_swap_b32 v132, v134
	v_permlane16_swap_b32 v133, v135
	v_permlane16_swap_b32 v136, v138
	v_permlane16_swap_b32 v137, v139
	v_lshlrev_b32_e32 v204, 16, v132
	v_and_b32_e32 v205, 0xffff0000, v132
	v_lshlrev_b32_e32 v206, 16, v133
	v_and_b32_e32 v207, 0xffff0000, v133
	v_pk_mul_f32 v[128:129], v[128:129], v[204:205]
	v_pk_mul_f32 v[130:131], v[130:131], v[206:207]
	v_lshlrev_b32_e32 v204, 16, v134
	v_and_b32_e32 v205, 0xffff0000, v134
	v_lshlrev_b32_e32 v206, 16, v135
	v_and_b32_e32 v207, 0xffff0000, v135
	v_pk_mul_f32 v[124:125], v[124:125], v[204:205]
	v_pk_mul_f32 v[126:127], v[126:127], v[206:207]
	v_lshlrev_b32_e32 v204, 16, v136
	v_and_b32_e32 v205, 0xffff0000, v136
	v_lshlrev_b32_e32 v206, 16, v137
	v_and_b32_e32 v207, 0xffff0000, v137
	v_pk_add_f32 v[128:129], v[128:129], v[204:205]
	v_pk_add_f32 v[130:131], v[130:131], v[206:207]
	v_lshlrev_b32_e32 v204, 16, v138
	v_and_b32_e32 v205, 0xffff0000, v138
	v_lshlrev_b32_e32 v206, 16, v139
	v_and_b32_e32 v207, 0xffff0000, v139
	v_pk_add_f32 v[124:125], v[124:125], v[204:205]
	v_pk_add_f32 v[126:127], v[126:127], v[206:207]
	v_cvt_pk_bf16_f32 v226, v128, v129
	v_cvt_pk_bf16_f32 v227, v130, v131
	v_cvt_pk_bf16_f32 v228, v124, v125
	v_cvt_pk_bf16_f32 v229, v126, v127
	s_nop 1
	v_permlane16_swap_b32 v226, v228
	v_permlane16_swap_b32 v227, v229
	global_store_dwordx4 v217, v[226:229], s[14:15] offset:0
	s_waitcnt vmcnt(5)
	v_permlane16_swap_b32 v140, v142
	v_permlane16_swap_b32 v141, v143
	v_permlane16_swap_b32 v144, v146
	v_permlane16_swap_b32 v145, v147
	v_lshlrev_b32_e32 v204, 16, v140
	v_and_b32_e32 v205, 0xffff0000, v140
	v_lshlrev_b32_e32 v206, 16, v141
	v_and_b32_e32 v207, 0xffff0000, v141
	v_pk_mul_f32 v[120:121], v[120:121], v[204:205]
	v_pk_mul_f32 v[122:123], v[122:123], v[206:207]
	v_lshlrev_b32_e32 v204, 16, v142
	v_and_b32_e32 v205, 0xffff0000, v142
	v_lshlrev_b32_e32 v206, 16, v143
	v_and_b32_e32 v207, 0xffff0000, v143
	v_pk_mul_f32 v[116:117], v[116:117], v[204:205]
	v_pk_mul_f32 v[118:119], v[118:119], v[206:207]
	v_lshlrev_b32_e32 v204, 16, v144
	v_and_b32_e32 v205, 0xffff0000, v144
	v_lshlrev_b32_e32 v206, 16, v145
	v_and_b32_e32 v207, 0xffff0000, v145
	v_pk_add_f32 v[120:121], v[120:121], v[204:205]
	v_pk_add_f32 v[122:123], v[122:123], v[206:207]
	v_lshlrev_b32_e32 v204, 16, v146
	v_and_b32_e32 v205, 0xffff0000, v146
	v_lshlrev_b32_e32 v206, 16, v147
	v_and_b32_e32 v207, 0xffff0000, v147
	v_pk_add_f32 v[116:117], v[116:117], v[204:205]
	v_pk_add_f32 v[118:119], v[118:119], v[206:207]
	v_cvt_pk_bf16_f32 v230, v120, v121
	v_cvt_pk_bf16_f32 v231, v122, v123
	v_cvt_pk_bf16_f32 v232, v116, v117
	v_cvt_pk_bf16_f32 v233, v118, v119
	s_nop 1
	v_permlane16_swap_b32 v230, v232
	v_permlane16_swap_b32 v231, v233
	global_store_dwordx4 v218, v[230:233], s[14:15] offset:0
	s_waitcnt vmcnt(4)
	v_permlane16_swap_b32 v148, v150
	v_permlane16_swap_b32 v149, v151
	v_permlane16_swap_b32 v152, v154
	v_permlane16_swap_b32 v153, v155
	v_lshlrev_b32_e32 v204, 16, v148
	v_and_b32_e32 v205, 0xffff0000, v148
	v_lshlrev_b32_e32 v206, 16, v149
	v_and_b32_e32 v207, 0xffff0000, v149
	v_pk_mul_f32 v[104:105], v[104:105], v[204:205]
	v_pk_mul_f32 v[106:107], v[106:107], v[206:207]
	v_lshlrev_b32_e32 v204, 16, v150
	v_and_b32_e32 v205, 0xffff0000, v150
	v_lshlrev_b32_e32 v206, 16, v151
	v_and_b32_e32 v207, 0xffff0000, v151
	v_pk_mul_f32 v[100:101], v[100:101], v[204:205]
	v_pk_mul_f32 v[102:103], v[102:103], v[206:207]
	v_lshlrev_b32_e32 v204, 16, v152
	v_and_b32_e32 v205, 0xffff0000, v152
	v_lshlrev_b32_e32 v206, 16, v153
	v_and_b32_e32 v207, 0xffff0000, v153
	v_pk_add_f32 v[104:105], v[104:105], v[204:205]
	v_pk_add_f32 v[106:107], v[106:107], v[206:207]
	v_lshlrev_b32_e32 v204, 16, v154
	v_and_b32_e32 v205, 0xffff0000, v154
	v_lshlrev_b32_e32 v206, 16, v155
	v_and_b32_e32 v207, 0xffff0000, v155
	v_pk_add_f32 v[100:101], v[100:101], v[204:205]
	v_pk_add_f32 v[102:103], v[102:103], v[206:207]
	v_cvt_pk_bf16_f32 v244, v104, v105
	v_cvt_pk_bf16_f32 v245, v106, v107
	v_cvt_pk_bf16_f32 v246, v100, v101
	v_cvt_pk_bf16_f32 v247, v102, v103
	s_nop 1
	v_permlane16_swap_b32 v244, v246
	v_permlane16_swap_b32 v245, v247
	global_store_dwordx4 v219, v[244:247], s[14:15] offset:0
	s_waitcnt vmcnt(3)
	v_permlane16_swap_b32 v156, v158
	v_permlane16_swap_b32 v157, v159
	v_permlane16_swap_b32 v160, v162
	v_permlane16_swap_b32 v161, v163
	v_lshlrev_b32_e32 v204, 16, v156
	v_and_b32_e32 v205, 0xffff0000, v156
	v_lshlrev_b32_e32 v206, 16, v157
	v_and_b32_e32 v207, 0xffff0000, v157
	v_pk_mul_f32 v[88:89], v[88:89], v[204:205]
	v_pk_mul_f32 v[90:91], v[90:91], v[206:207]
	v_lshlrev_b32_e32 v204, 16, v158
	v_and_b32_e32 v205, 0xffff0000, v158
	v_lshlrev_b32_e32 v206, 16, v159
	v_and_b32_e32 v207, 0xffff0000, v159
	v_pk_mul_f32 v[84:85], v[84:85], v[204:205]
	v_pk_mul_f32 v[86:87], v[86:87], v[206:207]
	v_lshlrev_b32_e32 v204, 16, v160
	v_and_b32_e32 v205, 0xffff0000, v160
	v_lshlrev_b32_e32 v206, 16, v161
	v_and_b32_e32 v207, 0xffff0000, v161
	v_pk_add_f32 v[88:89], v[88:89], v[204:205]
	v_pk_add_f32 v[90:91], v[90:91], v[206:207]
	v_lshlrev_b32_e32 v204, 16, v162
	v_and_b32_e32 v205, 0xffff0000, v162
	v_lshlrev_b32_e32 v206, 16, v163
	v_and_b32_e32 v207, 0xffff0000, v163
	v_pk_add_f32 v[84:85], v[84:85], v[204:205]
	v_pk_add_f32 v[86:87], v[86:87], v[206:207]
	v_cvt_pk_bf16_f32 v248, v88, v89
	v_cvt_pk_bf16_f32 v249, v90, v91
	v_cvt_pk_bf16_f32 v250, v84, v85
	v_cvt_pk_bf16_f32 v251, v86, v87
	s_nop 1
	v_permlane16_swap_b32 v248, v250
	v_permlane16_swap_b32 v249, v251
	global_store_dwordx4 v220, v[248:251], s[14:15] offset:0
.Lp5_done:
.LBB0_1216:
	s_and_b64 vcc, exec, s[0:1]
	s_mov_b64 s[0:1], -1
	s_cbranch_vccnz .LBB0_1125
	s_andn2_b64 vcc, exec, s[12:13]
	s_cbranch_vccnz .LBB0_1124
	s_barrier
	s_branch .LBB0_1124
